# attention QK phase: counted waits paired (one wait per two MFMAs) and a no-op scalar add dropped
# speedup vs baseline: 1.0046x; 1.0046x over previous
; #define MFMA(a, b, c) __builtin_amdgcn_mfma_f32_32x32x16_bf16((a), (b), (c), 0, 0, 0)
; template <int DV> ...
;     const float THR = 8.f;
;     f32x16 S[2];
; #pragma unroll
;     for (int sub = 0; sub < 2; sub++) {
;         const bf16x8 kf = *(const bf16x8*)(Kl + (sub * 32 + l31) * LROW + hh * 16);
;         S[sub] = MFMA(kf, qf[0], NEGM);
;     }
; #pragma unroll
;     for (int kk = 1; kk < 4; kk++)
; #pragma unroll
;         for (int sub = 0; sub < 2; sub++) {
;             const bf16x8 kf = *(const bf16x8*)(Kl + (sub * 32 + l31) * LROW + kk * 32 + hh * 16);
;             S[sub] = MFMA(kf, qf[kk], S[sub]);
;         }
;     if (domask) {
; #pragma unroll
;         for (int sub = 0; sub < 2; sub++)
; #pragma unroll
;             for (int r = 0; r < 16; r++) {
;                 const int d = qpos - (kpos0 + sub * 32 + (r & 3) + 8 * (r >> 2) + 4 * hh);
;                 S[sub][r] = (d <= 128 && d >= -128) ? S[sub][r] : -1e30f;
;             }
.LBB0_484:
	s_bitcmp1_b32 s16, 0
	s_cselect_b32 s16, 0x4800, 0
	v_add_u32_e32 v120, s16, v117
	ds_read_b128 v[192:195], v120
	ds_read_b128 v[196:199], v120 offset:4608
	ds_read_b128 v[200:203], v120 offset:32
	ds_read_b128 v[204:207], v120 offset:4640
	ds_read_b128 v[208:211], v120 offset:64
	ds_read_b128 v[212:215], v120 offset:4672
	ds_read_b128 v[216:219], v120 offset:96
	ds_read_b128 v[220:223], v120 offset:4704
	ds_read_b128 v[224:227], v120 offset:9216
	ds_read_b128 v[228:231], v120 offset:13824
	ds_read_b128 v[232:235], v120 offset:13856
	ds_read_b128 v[236:239], v120 offset:9248
	ds_read_b128 v[240:243], v120 offset:9280
	ds_read_b128 v[244:247], v120 offset:13888
	ds_read_b128 v[134:137], v120 offset:9312
	s_add_i32 s16, s77, s30
	s_addk_i32 s16, 0xfebe
	s_cmp_lt_u32 s16, 0xffffff5d
	s_cselect_b64 s[16:17], -1, 0
	s_and_b64 s[16:17], s[0:1], s[16:17]
	s_andn2_b64 vcc, exec, s[16:17]
	s_waitcnt lgkmcnt(13)
	v_mfma_f32_32x32x16_bf16 v[66:81], v[192:195], v[82:85], v[34:49]
	v_mfma_f32_32x32x16_bf16 v[50:65], v[196:199], v[82:85], v[34:49]
	ds_read_b128 v[138:141], v120 offset:13920
	s_waitcnt lgkmcnt(12)
	v_mfma_f32_32x32x16_bf16 v[66:81], v[200:203], v[86:89], v[66:81]
	v_mfma_f32_32x32x16_bf16 v[50:65], v[204:207], v[86:89], v[50:65]
	s_waitcnt lgkmcnt(10)
	v_mfma_f32_32x32x16_bf16 v[66:81], v[208:211], v[90:93], v[66:81]
	v_mfma_f32_32x32x16_bf16 v[50:65], v[212:215], v[90:93], v[50:65]
	s_waitcnt lgkmcnt(9)
	v_mfma_f32_32x32x16_bf16 v[66:81], v[216:219], v[94:97], v[66:81]
	s_waitcnt lgkmcnt(8)
	v_mfma_f32_32x32x16_bf16 v[50:65], v[220:223], v[94:97], v[50:65]
	s_cbranch_vccnz .LBB0_486
	v_add_u32_e32 v121, 59, v119
	s_movk_i32 s17, 0x101
	v_cmp_gt_u32_e32 vcc, s17, v121
	v_add_u32_e32 v121, s30, v118
	s_movk_i32 s16, 0xfefe
	s_nop 3
	v_cndmask_b32_e32 v66, v187, v66, vcc
	v_cmp_lt_u32_e32 vcc, s16, v121
	v_add_u32_e32 v121, 57, v119
	s_nop 0
	v_cndmask_b32_e32 v67, v187, v67, vcc
	v_cmp_gt_u32_e32 vcc, s17, v121
	v_add_u32_e32 v121, 56, v119
	s_nop 0
	v_cndmask_b32_e32 v68, v187, v68, vcc
	v_cmp_gt_u32_e32 vcc, s17, v121
	v_add_u32_e32 v121, 51, v119
	s_nop 0
	v_cndmask_b32_e32 v69, v187, v69, vcc
	v_cmp_gt_u32_e32 vcc, s17, v121
	v_add_u32_e32 v121, 50, v119
	s_nop 0
	v_cndmask_b32_e32 v70, v187, v70, vcc
	v_cmp_gt_u32_e32 vcc, s17, v121
	v_add_u32_e32 v121, 49, v119
	s_nop 0
	v_cndmask_b32_e32 v71, v187, v71, vcc
	v_cmp_gt_u32_e32 vcc, s17, v121
	v_add_u32_e32 v121, 48, v119
	s_nop 0
	v_cndmask_b32_e32 v72, v187, v72, vcc
	v_cmp_gt_u32_e32 vcc, s17, v121
	v_add_u32_e32 v121, 43, v119
	s_nop 0
	v_cndmask_b32_e32 v73, v187, v73, vcc
	v_cmp_gt_u32_e32 vcc, s17, v121
	v_add_u32_e32 v121, 42, v119
	s_nop 0
	v_cndmask_b32_e32 v74, v187, v74, vcc
	v_cmp_gt_u32_e32 vcc, s17, v121
	v_add_u32_e32 v121, 41, v119
	s_nop 0
	v_cndmask_b32_e32 v75, v187, v75, vcc
	v_cmp_gt_u32_e32 vcc, s17, v121
	v_add_u32_e32 v121, 40, v119
	s_nop 0
	v_cndmask_b32_e32 v76, v187, v76, vcc
	v_cmp_gt_u32_e32 vcc, s17, v121
	v_add_u32_e32 v121, 35, v119
	s_nop 0
	v_cndmask_b32_e32 v77, v187, v77, vcc
	v_cmp_gt_u32_e32 vcc, s17, v121
	v_add_u32_e32 v121, 34, v119
	s_nop 0
	v_cndmask_b32_e32 v78, v187, v78, vcc
	v_cmp_gt_u32_e32 vcc, s17, v121
	v_add_u32_e32 v121, 33, v119
	s_nop 0
	v_cndmask_b32_e32 v79, v187, v79, vcc
	v_cmp_gt_u32_e32 vcc, s17, v121
	v_add_u32_e32 v121, 32, v119
	s_nop 0
	v_cndmask_b32_e32 v80, v187, v80, vcc
	v_cmp_gt_u32_e32 vcc, s17, v121
	v_add_u32_e32 v121, 27, v119
	s_nop 0
	v_cndmask_b32_e32 v81, v187, v81, vcc
	v_cmp_gt_u32_e32 vcc, s17, v121
	v_add_u32_e32 v121, 26, v119
	s_nop 0
	v_cndmask_b32_e32 v50, v187, v50, vcc
	v_cmp_gt_u32_e32 vcc, s17, v121
	v_add_u32_e32 v121, 25, v119
	s_nop 0
	v_cndmask_b32_e32 v51, v187, v51, vcc
	v_cmp_gt_u32_e32 vcc, s17, v121
	v_add_u32_e32 v121, 24, v119
	s_nop 0
	v_cndmask_b32_e32 v52, v187, v52, vcc
	v_cmp_gt_u32_e32 vcc, s17, v121
	v_add_u32_e32 v121, 19, v119
	s_nop 0
	v_cndmask_b32_e32 v53, v187, v53, vcc
	v_cmp_gt_u32_e32 vcc, s17, v121
	v_add_u32_e32 v121, 18, v119
	s_nop 0
	v_cndmask_b32_e32 v54, v187, v54, vcc
	v_cmp_gt_u32_e32 vcc, s17, v121
	v_add_u32_e32 v121, 17, v119
	s_nop 0
	v_cndmask_b32_e32 v55, v187, v55, vcc
	v_cmp_gt_u32_e32 vcc, s17, v121
	v_add_u32_e32 v121, 16, v119
	s_nop 0
	v_cndmask_b32_e32 v56, v187, v56, vcc
	v_cmp_gt_u32_e32 vcc, s17, v121
	v_add_u32_e32 v121, 11, v119
	s_nop 0
	v_cndmask_b32_e32 v57, v187, v57, vcc
	v_cmp_gt_u32_e32 vcc, s17, v121
	v_add_u32_e32 v121, 10, v119
	s_nop 0
	v_cndmask_b32_e32 v58, v187, v58, vcc
	v_cmp_gt_u32_e32 vcc, s17, v121
	v_add_u32_e32 v121, 9, v119
	s_nop 0
	v_cndmask_b32_e32 v59, v187, v59, vcc
	v_cmp_gt_u32_e32 vcc, s17, v121
	v_add_u32_e32 v121, 8, v119
	s_nop 0
	v_cndmask_b32_e32 v60, v187, v60, vcc
	v_cmp_gt_u32_e32 vcc, s17, v121
	v_add_u32_e32 v121, 3, v119
	s_nop 0
	v_cndmask_b32_e32 v61, v187, v61, vcc
	v_cmp_gt_u32_e32 vcc, s17, v121
	v_add_u32_e32 v121, 2, v119
	s_nop 0
	v_cndmask_b32_e32 v62, v187, v62, vcc
	v_cmp_gt_u32_e32 vcc, s17, v121
	v_add_u32_e32 v121, 1, v119
	s_nop 0
	v_cndmask_b32_e32 v63, v187, v63, vcc
	v_cmp_gt_u32_e32 vcc, s17, v121
	s_nop 1
	v_cndmask_b32_e32 v64, v187, v64, vcc
	v_cmp_gt_u32_e32 vcc, s17, v119
	s_nop 1
	v_cndmask_b32_e32 v65, v187, v65, vcc

; #define MFMA(a, b, c) __builtin_amdgcn_mfma_f32_32x32x16_bf16((a), (b), (c), 0, 0, 0)
; template <int DV>
; __device__ __forceinline__ void attn_tile(const unsigned char* Kl, const unsigned char* Vl, const bf16x8 (&qf)[4], f32x16 (&O)[DV / 32], float& m, float& l,
;                                           int l31, int hh, bool domask, int qpos, int kpos0) {
;     ...
; #pragma unroll
;     for (int sub = 0; sub < 2; sub++)
; #pragma unroll
;         for (int r = 0; r < 16; r++) S[sub][r] = 0.f;
; #pragma unroll
;     for (int kk = 0; kk < 4; kk++)
; #pragma unroll
;         for (int sub = 0; sub < 2; sub++) {
;             const bf16x8 kf = *(const bf16x8*)(Kl + (sub * 32 + l31) * LROW + kk * 32 + hh * 16);
;             S[sub] = MFMA(kf, qf[kk], S[sub]);
;         }
;     if (domask) {
; #pragma unroll
;         for (int sub = 0; sub < 2; sub++)
; #pragma unroll
;             for (int r = 0; r < 16; r++) {
;                 const int d = qpos - (kpos0 + sub * 32 + (r & 3) + 8 * (r >> 2) + 4 * hh);
;                 S[sub][r] = (d <= 128 && d >= -128) ? S[sub][r] : -1e30f;
;             }
;     }
;     float mx = S[0][0];
; #pragma unroll
;     for (int sub = 0; sub < 2; sub++)
; #pragma unroll
;         for (int r = 0; r < 16; r++) mx = fmaxf(mx, S[sub][r]);
;     mx = fmaxf(mx, __shfl_xor(mx, 32));
;     const float mxs = mx * SL2;
;     if (__any(mxs > m + THR)) {
; template <bool DIFF>
; __device__ __forceinline__ void attn_unit(const Params& p, int layer, int mode, int bl, int hidx, int qblk, bool isctx, unsigned char* lds) {
;     ...
;     for (int it = 0; it < ntile; it++) {
;         const unsigned char* cur = lds + (it & 1) * BUFB;
;         const bool more = (it + 1 < ntile);
;         if (more) {
;             const int t0 = (it + 1 < 4) ? (it + 1) * 64 : start2 + (it + 1 - 4) * 64;
; #pragma unroll
;             for (int i = 0; i < NKM; i++) kr[i] = *(const u32x4*)(kp + (size_t)(t0 + lr) * INW + i * 64 + lc * 8);
; #pragma unroll
;             for (int i = 0; i < DV / 64; i++) vr[i] = *(const u32x4*)(vt + (size_t)(lr + i * 64) * TT + t0 + lc * 8);
;         }
;         const int tcur = (it < 4) ? it * 64 : start2 + (it - 4) * 64;
;         const int rel = (tcur - CTXL) - (DIFF ? 0 : (qblk * 64 + (wave >> 2) * 32));
;         if (DIFF) attn_tile<DV>(cur + cm * 9216, cur + KBYTES, qf, O, m, l, l31, hh, false, qpos, tcur - CTXL);
.LBB0_499:
	s_bitcmp1_b32 s24, 0
	s_cselect_b32 s8, 0x9000, 0
	s_add_i32 s9, s1, 0x100
	s_add_i32 s16, s15, s1
	s_cmp_lt_u32 s24, 3
	s_cselect_b32 s16, s9, s16
	s_ashr_i32 s17, s16, 31
	v_add_u32_e32 v0, s16, v146
	v_lshl_add_u64 v[14:15], s[16:17], 1, v[132:133]
	s_add_i32 s9, s8, s30
	v_mad_i64_i32 v[6:7], s[42:43], v0, s80, v[140:141]
	v_lshl_add_u64 v[10:11], v[14:15], 0, v[134:135]
	v_lshl_add_u64 v[14:15], v[14:15], 0, v[136:137]
	v_add3_u32 v0, s9, v191, v144
	global_load_dwordx4 v[2:5], v[6:7], off
	s_nop 0
	global_load_dwordx4 v[6:9], v[6:7], off offset:128
	s_nop 0
	global_load_dwordx4 v[10:13], v[10:11], off
	s_nop 0
	global_load_dwordx4 v[128:131], v[14:15], off
	v_add3_u32 v193, s8, v191, v144
	ds_read_b128 v[194:197], v0
	ds_read_b128 v[198:201], v0 offset:4608
	ds_read_b128 v[202:205], v0 offset:32
	ds_read_b128 v[206:209], v0 offset:4640
	ds_read_b128 v[210:213], v0 offset:64
	ds_read_b128 v[214:217], v0 offset:4672
	ds_read_b128 v[218:221], v0 offset:96
	ds_read_b128 v[222:225], v0 offset:4704
	s_waitcnt lgkmcnt(6)
	v_mfma_f32_32x32x16_bf16 v[96:111], v[194:197], v[124:127], v[234:249]
	v_mfma_f32_32x32x16_bf16 v[80:95], v[198:201], v[124:127], v[234:249]
	ds_read_b128 v[226:229], v193 offset:18432
	ds_read_b128 v[230:233], v193 offset:23040
	ds_read_b128 v[156:159], v193 offset:27648
	ds_read_b128 v[160:163], v193 offset:32256
	s_waitcnt lgkmcnt(8)
	v_mfma_f32_32x32x16_bf16 v[96:111], v[202:205], v[120:123], v[96:111]
	v_mfma_f32_32x32x16_bf16 v[80:95], v[206:209], v[120:123], v[80:95]
	ds_read_b128 v[194:197], v193 offset:18464
	ds_read_b128 v[198:201], v193 offset:23072
	ds_read_b128 v[202:205], v193 offset:27680
	ds_read_b128 v[206:209], v193 offset:32288
	s_waitcnt lgkmcnt(10)
	v_mfma_f32_32x32x16_bf16 v[96:111], v[210:213], v[116:119], v[96:111]
	v_mfma_f32_32x32x16_bf16 v[80:95], v[214:217], v[116:119], v[80:95]
	s_waitcnt lgkmcnt(9)
	v_mfma_f32_32x32x16_bf16 v[96:111], v[218:221], v[112:115], v[96:111]
	s_waitcnt lgkmcnt(8)
	v_mfma_f32_32x32x16_bf16 v[80:95], v[222:225], v[112:115], v[80:95]
	ds_read_b128 v[210:213], v193 offset:18496
	ds_read_b128 v[214:217], v193 offset:23104
	ds_read_b128 v[218:221], v193 offset:27712
	ds_read_b128 v[222:225], v193 offset:32320
	s_nop 5
	v_max3_f32 v0, v96, v97, v98
	v_max3_f32 v0, v0, v99, v100
	v_max3_f32 v0, v0, v101, v102
	v_max3_f32 v0, v0, v103, v104
	v_max3_f32 v14, v80, v81, v82
	v_max3_f32 v0, v0, v105, v106
	v_max3_f32 v14, v14, v83, v84
	v_max3_f32 v0, v0, v107, v108
	v_max3_f32 v14, v14, v85, v86
	v_max3_f32 v0, v0, v109, v110
	v_max3_f32 v14, v14, v87, v88
	v_max3_f32 v14, v14, v89, v90
	v_max3_f32 v14, v14, v91, v92
	v_max3_f32 v14, v14, v93, v94
	v_max3_f32 v0, v0, v111, v95
	v_max_f32_e32 v0, v0, v14
	v_mov_b32_e32 v14, v0
	s_nop 1
	v_permlane32_swap_b32_e32 v0, v14
	v_max_f32_e32 v0, v0, v14
	s_cmp_eq_u32 s24, 0
	s_cbranch_scc1 .Lb_resc_first
	v_mov_b32_e32 v14, 0x41000000
	v_cmp_gt_f32_e32 vcc, v0, v14
	s_cbranch_vccz .LBB0_498
	v_max_f32_e32 v0, 0, v0
